# G1 phase: all global loads of an item issued up front (prefetch registers), counted waits at the use sites
# speedup vs baseline: 1.0015x; 1.0004x over previous
; __device__ __forceinline__ unsigned cvt_pk_bf16(float lo, float hi) { unsigned r; asm volatile("v_cvt_pk_bf16_f32 %0, %1, %2" : "=v"(r) : "v"(lo), "v"(hi)); return r; }
; __device__ __forceinline__ void gla_g1(const Params& P, unsigned char* lds) {
;     ...
; #pragma unroll
;         for (int mt = 0; mt < 8; ++mt)
; #pragma unroll
;             for (int nt = 0; nt < 2; ++nt) { u32x2 w; w.x = cvt_pk_bf16(acc[mt][nt][0], acc[mt][nt][1]); w.y = cvt_pk_bf16(acc[mt][nt][2], acc[mt][nt][3]);
;                 *(u32x2*)(KVT + ((size_t)it * 256 + 32 * wid + 16 * nt + fr) * 128 + 16 * mt + 4 * fq) = w; }
;         __syncthreads();
.LBB0_1961:
	s_waitcnt vmcnt(0)
	s_ashr_i32 s79, s78, 31
	s_lshl_b64 s[16:17], s[78:79], 16
	v_cvt_pk_bf16_f32 v56, v56, v57
	v_cvt_pk_bf16_f32 v57, v58, v59
	v_lshl_add_u64 v[58:59], s[16:17], 0, v[90:91]
	v_lshl_add_u64 v[150:151], v[72:73], 0, v[58:59]
	v_or_b32_e32 v58, 0x1000, v58
	global_store_dwordx2 v[150:151], v[56:57], off
	v_cvt_pk_bf16_f32 v56, v60, v61
	v_lshl_add_u64 v[60:61], v[72:73], 0, v[58:59]
	v_cvt_pk_bf16_f32 v57, v62, v63
	global_store_dwordx2 v[60:61], v[56:57], off
	v_cvt_pk_bf16_f32 v48, v48, v49
	v_cvt_pk_bf16_f32 v49, v50, v51
	v_lshl_add_u64 v[50:51], v[74:75], 0, v[58:59]
	global_store_dwordx2 v[150:151], v[48:49], off offset:32
	v_cvt_pk_bf16_f32 v48, v52, v53
	v_cvt_pk_bf16_f32 v49, v54, v55
	global_store_dwordx2 v[50:51], v[48:49], off
	v_cvt_pk_bf16_f32 v40, v40, v41
	v_cvt_pk_bf16_f32 v41, v42, v43
	v_lshl_add_u64 v[42:43], v[76:77], 0, v[58:59]
	global_store_dwordx2 v[150:151], v[40:41], off offset:64
	v_cvt_pk_bf16_f32 v40, v44, v45
	v_cvt_pk_bf16_f32 v41, v46, v47
	global_store_dwordx2 v[42:43], v[40:41], off
	v_cvt_pk_bf16_f32 v32, v32, v33
	v_cvt_pk_bf16_f32 v33, v34, v35
	v_lshl_add_u64 v[34:35], v[78:79], 0, v[58:59]
	global_store_dwordx2 v[150:151], v[32:33], off offset:96
	v_cvt_pk_bf16_f32 v32, v36, v37
	v_cvt_pk_bf16_f32 v33, v38, v39
	global_store_dwordx2 v[34:35], v[32:33], off
	v_cvt_pk_bf16_f32 v24, v24, v25
	v_cvt_pk_bf16_f32 v25, v26, v27
	v_lshl_add_u64 v[26:27], v[80:81], 0, v[58:59]
	global_store_dwordx2 v[150:151], v[24:25], off offset:128
	v_cvt_pk_bf16_f32 v24, v28, v29
	v_cvt_pk_bf16_f32 v25, v30, v31
	global_store_dwordx2 v[26:27], v[24:25], off
	v_cvt_pk_bf16_f32 v16, v16, v17
	v_cvt_pk_bf16_f32 v17, v18, v19
	v_lshl_add_u64 v[18:19], v[82:83], 0, v[58:59]
	global_store_dwordx2 v[150:151], v[16:17], off offset:160
	v_cvt_pk_bf16_f32 v16, v20, v21
	v_cvt_pk_bf16_f32 v17, v22, v23
	global_store_dwordx2 v[18:19], v[16:17], off
	v_cvt_pk_bf16_f32 v8, v8, v9
	v_cvt_pk_bf16_f32 v9, v10, v11
	v_lshl_add_u64 v[10:11], v[84:85], 0, v[58:59]
	s_add_i32 s78, s78, s58
	s_add_i32 s86, s86, s87
	s_add_i32 s88, s88, s89
	s_add_i32 s90, s90, s91
	global_store_dwordx2 v[150:151], v[8:9], off offset:192
	v_cvt_pk_bf16_f32 v8, v12, v13
	v_cvt_pk_bf16_f32 v9, v14, v15
	global_store_dwordx2 v[10:11], v[8:9], off
	v_cvt_pk_bf16_f32 v0, v0, v1
	v_cvt_pk_bf16_f32 v1, v2, v3
	v_lshl_add_u64 v[2:3], v[86:87], 0, v[58:59]
	s_cmpk_lt_i32 s78, 0x440
	global_store_dwordx2 v[150:151], v[0:1], off offset:224
	v_cvt_pk_bf16_f32 v0, v4, v5
	v_cvt_pk_bf16_f32 v1, v6, v7
	global_store_dwordx2 v[2:3], v[0:1], off
	s_barrier
	s_cbranch_scc0 .LBB0_1978

; __device__ __forceinline__ void compute_b(const Params& P, const Item& I, unsigned char* lds) {
;     ...
;     if (tid < 256) { const int t = tid >> 2, tc = t < I.L ? t : I.L - 1; f32x4 v = *(const f32x4*)(gr + (size_t)(I.row0 + tc) * 16 + (tid & 3) * 4); if (t >= I.L) v = (f32x4){0.f, 0.f, 0.f, 0.f}; *(f32x4*)(grs + tid * 4) = v; }
;     const int dk = tid & 127, tq = tid >> 7;
;     float wc[16];
; #pragma unroll
;     for (int r = 0; r < 16; ++r) wc[r] = P.in[14][r * KEYD + I.h * DK + dk];
;     const float bias = P.in[15][I.h * DK + dk];
;     __syncthreads();
;     float bl[16]; float run = 0.f;
; #pragma unroll
;     for (int i = 0; i < 16; ++i) { const int t = tq * 16 + i; float a = bias;
; #pragma unroll
;         for (int r = 0; r < 16; ++r) a += grs[t * 16 + r] * wc[r];
;         const float ls = fminf(a, 0.f) - __logf(1.0f + __expf(-fabsf(a)));
;         run += (t < I.L) ? ls * (1.0f / 16.0f) : 0.f; bl[i] = run; }
;     qt[tq * 128 + dk] = run;
;     __syncthreads();
;     float off = 0.f;
; #pragma unroll
;     for (int q = 0; q < 3; ++q) if (q < tq) off += qt[q * 128 + dk];
; #pragma unroll
;     for (int i = 0; i < 16; ++i) bsh[(tq * 16 + i) * 128 + dk] = bl[i] + off;
;     __syncthreads();
; }
; __device__ __forceinline__ void gla_g1(const Params& P, unsigned char* lds) {
;     const int tid = threadIdx.x, wid = tid >> 6, lane = tid & 63, fr = lane & 15, fq = lane >> 4;
;     const bf16_t* kg = (const bf16_t*)(P.ws + O_K); const bf16_t* vT = (const bf16_t*)(P.ws + O_VT);
;     bf16_t* KVT = (bf16_t*)(P.ws + O_KVT); float* dec = (float*)(P.ws + O_DEC);
;     const float* bsh = (const float*)(lds + L_BSH); bf16_t* kT = (bf16_t*)(lds + L_KT);
;     for (int it = blockIdx.x; it < NITEM; it += gridDim.x) {
;         const Item I = decode_item(it);
;         compute_b(P, I, lds);
;         { const int dk = tid & 127, tq = tid >> 7; const float blast = bsh[63 * 128 + dk]; float ke[16];
;             bf16_t kraw[16];
; #pragma unroll
;             for (int i = 0; i < 16; ++i) { const int t = tq * 16 + i, tc = t < I.L ? t : I.L - 1; kraw[i] = kg[(size_t)(I.row0 + tc) * KEYD + I.h * DK + dk]; }
; #pragma unroll
;             for (int i = 0; i < 16; ++i) { const int t = tq * 16 + i; const float kv = bf1(kraw[i]) * __expf(blast - bsh[t * 128 + dk]); ke[i] = t < I.L ? kv : 0.f; }
.LBB0_1964:
	s_add_i32 s99, s64, -1
	s_and_b32 s98, s18, 3
	s_mov_b64 s[100:101], exec
	s_and_b64 exec, exec, s[6:7]
	s_cbranch_execz .Lg1pf_nogr
	v_min_u32_e32 v242, s99, v92
	v_add_u32_e32 v242, s82, v242
	v_ashrrev_i32_e32 v243, 31, v242
	v_lshlrev_b64 v[242:243], 6, v[242:243]
	v_lshl_add_u64 v[242:243], v[88:89], 0, v[242:243]
	global_load_dwordx4 v[190:193], v[242:243], off
.Lg1pf_nogr:
	s_mov_b64 exec, s[100:101]
	s_lshl_b32 s100, s98, 7
	v_or_b32_e32 v242, s100, v94
	v_lshlrev_b32_e32 v242, 2, v242
	global_load_dword v194, v242, s[60:61]
	global_load_dword v195, v242, s[60:61] offset:2048
	global_load_dword v211, v242, s[62:63]
	v_add_u32_e32 v243, 0x1000, v242
	global_load_dword v196, v243, s[60:61]
	global_load_dword v197, v243, s[60:61] offset:2048
	v_add_u32_e32 v243, 0x2000, v242
	global_load_dword v198, v243, s[60:61]
	global_load_dword v199, v243, s[60:61] offset:2048
	v_add_u32_e32 v243, 0x3000, v242
	global_load_dword v200, v243, s[60:61]
	global_load_dword v201, v243, s[60:61] offset:2048
	v_add_u32_e32 v243, 0x4000, v242
	global_load_dword v202, v243, s[60:61]
	global_load_dword v203, v243, s[60:61] offset:2048
	v_add_u32_e32 v243, 0x5000, v242
	global_load_dword v204, v243, s[60:61]
	global_load_dword v205, v243, s[60:61] offset:2048
	v_add_u32_e32 v243, 0x6000, v242
	global_load_dword v206, v243, s[60:61]
	global_load_dword v207, v243, s[60:61] offset:2048
	v_add_u32_e32 v243, 0x7000, v242
	global_load_dword v208, v243, s[60:61]
	global_load_dword v209, v243, s[60:61] offset:2048
	s_add_u32 s100, s54, 0x614dc00
	s_addc_u32 s101, s55, 0
	v_mov_b32_e32 v241, s98
	v_lshlrev_b32_e32 v241, 8, v241
	v_lshl_add_u32 v241, v94, 1, v241
	v_min_i32_e32 v243, s99, v95
	v_add_u32_e32 v243, s82, v243
	v_lshl_add_u32 v243, v243, 10, v241
	global_load_ushort v212, v243, s[100:101]
	v_min_i32_e32 v243, s99, v96
	v_add_u32_e32 v243, s82, v243
	v_lshl_add_u32 v243, v243, 10, v241
	global_load_ushort v213, v243, s[100:101]
	v_min_i32_e32 v243, s99, v97
	v_add_u32_e32 v243, s82, v243
	v_lshl_add_u32 v243, v243, 10, v241
	global_load_ushort v214, v243, s[100:101]
	v_min_i32_e32 v243, s99, v98
	v_add_u32_e32 v243, s82, v243
	v_lshl_add_u32 v243, v243, 10, v241
	global_load_ushort v215, v243, s[100:101]
	v_min_i32_e32 v243, s99, v99
	v_add_u32_e32 v243, s82, v243
	v_lshl_add_u32 v243, v243, 10, v241
	global_load_ushort v216, v243, s[100:101]
	v_min_i32_e32 v243, s99, v100
	v_add_u32_e32 v243, s82, v243
	v_lshl_add_u32 v243, v243, 10, v241
	global_load_ushort v217, v243, s[100:101]
	v_min_i32_e32 v243, s99, v101
	v_add_u32_e32 v243, s82, v243
	v_lshl_add_u32 v243, v243, 10, v241
	global_load_ushort v218, v243, s[100:101]
	v_min_i32_e32 v243, s99, v102
	v_add_u32_e32 v243, s82, v243
	v_lshl_add_u32 v243, v243, 10, v241
	global_load_ushort v219, v243, s[100:101]
	v_min_i32_e32 v243, s99, v103
	v_add_u32_e32 v243, s82, v243
	v_lshl_add_u32 v243, v243, 10, v241
	global_load_ushort v220, v243, s[100:101]
	v_min_i32_e32 v243, s99, v104
	v_add_u32_e32 v243, s82, v243
	v_lshl_add_u32 v243, v243, 10, v241
	global_load_ushort v221, v243, s[100:101]
	v_min_i32_e32 v243, s99, v105
	v_add_u32_e32 v243, s82, v243
	v_lshl_add_u32 v243, v243, 10, v241
	global_load_ushort v222, v243, s[100:101]
	v_min_i32_e32 v243, s99, v106
	v_add_u32_e32 v243, s82, v243
	v_lshl_add_u32 v243, v243, 10, v241
	global_load_ushort v223, v243, s[100:101]
	v_min_i32_e32 v243, s99, v107
	v_add_u32_e32 v243, s82, v243
	v_lshl_add_u32 v243, v243, 10, v241
	global_load_ushort v224, v243, s[100:101]
	v_min_i32_e32 v243, s99, v108
	v_add_u32_e32 v243, s82, v243
	v_lshl_add_u32 v243, v243, 10, v241
	global_load_ushort v225, v243, s[100:101]
	v_min_i32_e32 v243, s99, v109
	v_add_u32_e32 v243, s82, v243
	v_lshl_add_u32 v243, v243, 10, v241
	global_load_ushort v226, v243, s[100:101]
	v_min_i32_e32 v243, s99, v110
	v_add_u32_e32 v243, s82, v243
	v_lshl_add_u32 v243, v243, 10, v241
	global_load_ushort v227, v243, s[100:101]
	s_mov_b32 s100, s3
	s_mov_b32 s101, s85
	v_lshl_add_u32 v243, s98, 8, v116
	v_mul_u32_u24_e32 v243, 0x8280, v243
	v_cmp_gt_u32_e32 vcc, s64, v70
	s_nop 1
	v_cndmask_b32_e32 v242, 0, v70, vcc
	v_add_u32_e32 v242, s82, v242
	v_lshl_add_u32 v242, v242, 1, v243
	global_load_dwordx4 v[228:231], v242, s[100:101]
	v_add_u32_e32 v241, 0x82800, v242
	global_load_dwordx4 v[232:235], v241, s[100:101]
	v_cmp_gt_u32_e32 vcc, s64, v71
	s_nop 1
	v_cndmask_b32_e32 v242, 0, v71, vcc
	v_add_u32_e32 v242, s82, v242
	v_lshl_add_u32 v242, v242, 1, v243
	global_load_dwordx4 v[236:239], v242, s[100:101]
	v_add_u32_e32 v241, 0x82800, v242
	global_load_dwordx4 v[244:247], v241, s[100:101]
	s_and_saveexec_b64 s[16:17], s[6:7]
	s_cbranch_execz .LBB0_1966
.LBB0_1965:
	s_add_i32 s19, s64, -1
	v_min_u32_e32 v0, s19, v92
	v_add_u32_e32 v0, s82, v0
	v_ashrrev_i32_e32 v1, 31, v0
	v_lshlrev_b64 v[0:1], 6, v[0:1]
	v_lshl_add_u64 v[0:1], v[88:89], 0, v[0:1]
	v_cmp_gt_u32_e32 vcc, s64, v92
	s_waitcnt vmcnt(37)
	s_nop 0
	v_cndmask_b32_e32 v3, 0, v193, vcc
	v_cndmask_b32_e32 v2, 0, v192, vcc
	v_cndmask_b32_e32 v1, 0, v191, vcc
	v_cndmask_b32_e32 v0, 0, v190, vcc
	ds_write_b128 v93, v[0:3]
; __device__ __forceinline__ void compute_b(const Params& P, const Item& I, unsigned char* lds) {
;     ...
;     const int dk = tid & 127, tq = tid >> 7;
;     float wc[16];
; #pragma unroll
;     for (int r = 0; r < 16; ++r) wc[r] = P.in[14][r * KEYD + I.h * DK + dk];
;     const float bias = P.in[15][I.h * DK + dk];
;     __syncthreads();
;     float bl[16]; float run = 0.f;
; #pragma unroll
;     for (int i = 0; i < 16; ++i) { const int t = tq * 16 + i; float a = bias;
; #pragma unroll
;         for (int r = 0; r < 16; ++r) a += grs[t * 16 + r] * wc[r];
;         const float ls = fminf(a, 0.f) - __logf(1.0f + __expf(-fabsf(a)));
;         run += (t < I.L) ? ls * (1.0f / 16.0f) : 0.f; bl[i] = run; }
.LBB0_1966:
	s_or_b64 exec, exec, s[16:17]
	s_and_b32 s65, s18, 3
	s_lshl_b32 s76, s65, 7
	v_or_b32_e32 v0, s76, v94
	v_lshlrev_b32_e32 v64, 2, v0
	v_lshl_add_u64 v[18:19], s[60:61], 0, v[64:65]
	v_add_co_u32_e32 v4, vcc, 0x1000, v18
	s_nop 1
	v_addc_co_u32_e32 v5, vcc, 0, v19, vcc
	v_add_co_u32_e32 v6, vcc, 0x2000, v18
	s_nop 1
	v_addc_co_u32_e32 v7, vcc, 0, v19, vcc
	v_add_co_u32_e32 v8, vcc, s92, v18
	s_nop 1
	v_addc_co_u32_e32 v9, vcc, 0, v19, vcc
	v_add_co_u32_e32 v20, vcc, 0x4000, v18
	s_nop 1
	v_addc_co_u32_e32 v21, vcc, 0, v19, vcc
	s_nop 0
	v_add_co_u32_e32 v8, vcc, 0x5000, v18
	s_nop 1
	v_addc_co_u32_e32 v9, vcc, 0, v19, vcc
	v_add_co_u32_e32 v20, vcc, 0x6000, v18
	s_nop 1
	v_addc_co_u32_e32 v21, vcc, 0, v19, vcc
	s_nop 0
	v_add_co_u32_e32 v18, vcc, 0x7000, v18
	s_nop 1
	v_addc_co_u32_e32 v19, vcc, 0, v19, vcc
	s_waitcnt vmcnt(20)
	v_mov_b32_e32 v2, v194
	v_mov_b32_e32 v0, v195
	v_mov_b32_e32 v16, v196
	v_mov_b32_e32 v15, v197
	v_mov_b32_e32 v13, v198
	v_mov_b32_e32 v10, v199
	v_mov_b32_e32 v7, v200
	v_mov_b32_e32 v5, v201
	v_mov_b32_e32 v4, v202
	v_mov_b32_e32 v3, v203
	v_mov_b32_e32 v14, v204
	v_mov_b32_e32 v11, v205
	v_mov_b32_e32 v8, v206
	v_mov_b32_e32 v6, v207
	v_mov_b32_e32 v12, v208
	v_mov_b32_e32 v9, v209
	v_mov_b32_e32 v1, v211
	s_waitcnt lgkmcnt(0)
	s_barrier
	ds_read_b128 v[18:21], v117
	ds_read_b128 v[22:25], v117 offset:16
	ds_read_b128 v[26:29], v117 offset:32
	ds_read_b128 v[30:33], v117 offset:48
	ds_read_b128 v[34:37], v118
	ds_read_b128 v[38:41], v118 offset:16
	ds_read_b128 v[42:45], v118 offset:32
	ds_read_b128 v[46:49], v118 offset:48
	s_waitcnt lgkmcnt(7)
	v_fma_f32 v17, v2, v18, v1
	v_fmac_f32_e32 v17, v0, v19
	v_fmac_f32_e32 v17, v16, v20
	v_fmac_f32_e32 v17, v15, v21
	s_waitcnt lgkmcnt(6)
	v_fmac_f32_e32 v17, v13, v22
	v_fmac_f32_e32 v17, v10, v23
	v_fmac_f32_e32 v17, v7, v24
	v_fmac_f32_e32 v17, v5, v25
	s_waitcnt lgkmcnt(5)
	v_fmac_f32_e32 v17, v4, v26
	v_fmac_f32_e32 v17, v3, v27
	s_waitcnt lgkmcnt(3)
	v_fma_f32 v18, v2, v34, v1
	v_fmac_f32_e32 v18, v0, v35
	v_fmac_f32_e32 v18, v16, v36
	v_fmac_f32_e32 v18, v15, v37
	s_waitcnt lgkmcnt(2)
	v_fmac_f32_e32 v18, v13, v38
	v_fmac_f32_e32 v18, v10, v39
	v_fmac_f32_e32 v17, v14, v28
	v_fmac_f32_e32 v17, v11, v29
	v_fmac_f32_e32 v17, v8, v30
	v_fmac_f32_e32 v17, v6, v31
	v_fmac_f32_e32 v18, v7, v40
	v_fmac_f32_e32 v18, v5, v41
	s_waitcnt lgkmcnt(1)
	v_fmac_f32_e32 v18, v4, v42
	v_fmac_f32_e32 v18, v3, v43
	v_fmac_f32_e32 v17, v12, v32
	v_fmac_f32_e32 v17, v9, v33
	v_mul_f32_e64 v19, |v17|, s93
	v_exp_f32_e32 v19, v19
	v_fmac_f32_e32 v18, v14, v44
	v_fmac_f32_e32 v18, v11, v45
	s_waitcnt lgkmcnt(0)
	v_fmac_f32_e32 v18, v8, v46
	v_add_f32_e32 v19, 1.0, v19
	v_cmp_gt_f32_e32 vcc, s94, v19
	v_fmac_f32_e32 v18, v6, v47
	v_fmac_f32_e32 v18, v12, v48
	v_cndmask_b32_e64 v21, 0, 32, vcc
	v_ldexp_f32 v19, v19, v21
	v_log_f32_e32 v19, v19
	v_fmac_f32_e32 v18, v9, v49
	v_mul_f32_e64 v20, |v18|, s93
	v_exp_f32_e32 v20, v20
	v_mul_f32_e32 v22, 0x3f317217, v19
	v_fma_f32 v22, v19, s95, -v22
	v_fmac_f32_e32 v22, 0x3377d1cf, v19
	v_cndmask_b32_e32 v21, 0, v148, vcc
	v_fmac_f32_e32 v22, 0x3f317217, v19
	v_cmp_lt_f32_e64 vcc, |v19|, s96
	v_add_f32_e32 v20, 1.0, v20
	v_min_f32_e32 v17, 0, v17
	v_cndmask_b32_e32 v19, v19, v22, vcc
	v_sub_f32_e32 v19, v19, v21
	v_cmp_gt_f32_e64 s[16:17], s94, v20
	v_sub_f32_e32 v17, v17, v19
	v_min_f32_e32 v34, 0, v18
	v_cndmask_b32_e64 v19, 0, 32, s[16:17]
	v_ldexp_f32 v19, v20, v19
	v_log_f32_e32 v19, v19
	v_cndmask_b32_e64 v36, 0, v148, s[16:17]
	v_cmp_gt_u32_e64 s[16:17], s64, v96
	v_fma_f32 v17, v17, s97, 0
	v_mul_f32_e32 v18, 0x3f317217, v19
	v_fma_f32 v18, v19, s95, -v18
	v_fmac_f32_e32 v18, 0x3377d1cf, v19
	v_fmac_f32_e32 v18, 0x3f317217, v19
	v_cmp_lt_f32_e64 s[18:19], |v19|, s96
	v_cmp_gt_u32_e32 vcc, s64, v95
	s_nop 0
	v_cndmask_b32_e64 v35, v19, v18, s[18:19]
	ds_read_b128 v[18:21], v119
	ds_read_b128 v[22:25], v119 offset:16
	ds_read_b128 v[26:29], v119 offset:32
	ds_read_b128 v[30:33], v119 offset:48
	v_cndmask_b32_e32 v17, 0, v17, vcc
	s_waitcnt lgkmcnt(3)
	v_fma_f32 v37, v2, v18, v1
	v_fmac_f32_e32 v37, v0, v19
	v_fmac_f32_e32 v37, v16, v20
	v_fmac_f32_e32 v37, v15, v21
	s_waitcnt lgkmcnt(2)
	v_fmac_f32_e32 v37, v13, v22
	v_fmac_f32_e32 v37, v10, v23
	v_fmac_f32_e32 v37, v7, v24
	v_fmac_f32_e32 v37, v5, v25
	s_waitcnt lgkmcnt(1)
	v_fmac_f32_e32 v37, v4, v26
	v_fmac_f32_e32 v37, v3, v27
	v_fmac_f32_e32 v37, v14, v28
	v_fmac_f32_e32 v37, v11, v29
	s_waitcnt lgkmcnt(0)
	v_fmac_f32_e32 v37, v8, v30
	v_fmac_f32_e32 v37, v6, v31
	v_fmac_f32_e32 v37, v12, v32
	v_fmac_f32_e32 v37, v9, v33
	v_mul_f32_e64 v18, |v37|, s93
	v_exp_f32_e32 v18, v18
	v_sub_f32_e32 v19, v35, v36
	v_sub_f32_e32 v19, v34, v19
	v_mul_f32_e32 v19, 0x3d800000, v19
	v_add_f32_e32 v18, 1.0, v18
	v_cmp_gt_f32_e64 s[18:19], s94, v18
	s_nop 1
	v_cndmask_b32_e64 v20, 0, 32, s[18:19]
	v_ldexp_f32 v18, v18, v20
	v_log_f32_e32 v20, v18
	v_cndmask_b32_e64 v18, 0, v19, s[16:17]
	v_min_f32_e32 v19, 0, v37
	v_cndmask_b32_e64 v37, 0, v148, s[18:19]
	v_mul_f32_e32 v21, 0x3f317217, v20
	v_fma_f32 v21, v20, s95, -v21
	v_fmac_f32_e32 v21, 0x3377d1cf, v20
	v_fmac_f32_e32 v21, 0x3f317217, v20
	v_cmp_lt_f32_e64 s[20:21], |v20|, s96
	v_cmp_gt_u32_e64 s[18:19], s64, v97
	v_add_f32_e32 v18, v17, v18
	v_cndmask_b32_e64 v36, v20, v21, s[20:21]
	ds_read_b128 v[20:23], v120
	ds_read_b128 v[24:27], v120 offset:16
	ds_read_b128 v[28:31], v120 offset:32
	ds_read_b128 v[32:35], v120 offset:48
	s_waitcnt lgkmcnt(3)
	v_fma_f32 v20, v2, v20, v1
	v_fmac_f32_e32 v20, v0, v21
	v_fmac_f32_e32 v20, v16, v22
	v_fmac_f32_e32 v20, v15, v23
	s_waitcnt lgkmcnt(2)
; __device__ __forceinline__ void compute_b(const Params& P, const Item& I, unsigned char* lds) {
;     ...
;     float bl[16]; float run = 0.f;
; #pragma unroll
;     for (int i = 0; i < 16; ++i) { const int t = tq * 16 + i; float a = bias;
; #pragma unroll
;         for (int r = 0; r < 16; ++r) a += grs[t * 16 + r] * wc[r];
;         const float ls = fminf(a, 0.f) - __logf(1.0f + __expf(-fabsf(a)));
;         run += (t < I.L) ? ls * (1.0f / 16.0f) : 0.f; bl[i] = run; }
	v_fmac_f32_e32 v20, v13, v24
	v_fmac_f32_e32 v20, v10, v25
	v_fmac_f32_e32 v20, v7, v26
	v_fmac_f32_e32 v20, v5, v27
	s_waitcnt lgkmcnt(1)
	v_fmac_f32_e32 v20, v4, v28
	v_fmac_f32_e32 v20, v3, v29
	v_fmac_f32_e32 v20, v14, v30
	v_fmac_f32_e32 v20, v11, v31
	s_waitcnt lgkmcnt(0)
	v_fmac_f32_e32 v20, v8, v32
	v_fmac_f32_e32 v20, v6, v33
	v_fmac_f32_e32 v20, v12, v34
	v_fmac_f32_e32 v20, v9, v35
	v_mul_f32_e64 v21, |v20|, s93
	v_exp_f32_e32 v21, v21
	v_sub_f32_e32 v22, v36, v37
	v_sub_f32_e32 v19, v19, v22
	v_min_f32_e32 v36, 0, v20
	v_add_f32_e32 v21, 1.0, v21
	v_cmp_gt_f32_e64 s[20:21], s94, v21
	v_mul_f32_e32 v19, 0x3d800000, v19
	v_cndmask_b32_e64 v19, 0, v19, s[18:19]
	v_cndmask_b32_e64 v22, 0, 32, s[20:21]
	v_ldexp_f32 v21, v21, v22
	v_log_f32_e32 v21, v21
	v_cndmask_b32_e64 v38, 0, v148, s[20:21]
	v_cmp_gt_u32_e64 s[20:21], s64, v98
	v_add_f32_e32 v19, v18, v19
	v_mul_f32_e32 v20, 0x3f317217, v21
	v_fma_f32 v20, v21, s95, -v20
	v_fmac_f32_e32 v20, 0x3377d1cf, v21
	v_fmac_f32_e32 v20, 0x3f317217, v21
	v_cmp_lt_f32_e64 s[22:23], |v21|, s96
	s_nop 1
	v_cndmask_b32_e64 v37, v21, v20, s[22:23]
	ds_read_b128 v[20:23], v121
	ds_read_b128 v[24:27], v121 offset:16
	ds_read_b128 v[28:31], v121 offset:32
	ds_read_b128 v[32:35], v121 offset:48
	s_waitcnt lgkmcnt(3)
	v_fma_f32 v39, v2, v20, v1
	v_fmac_f32_e32 v39, v0, v21
	v_fmac_f32_e32 v39, v16, v22
	v_fmac_f32_e32 v39, v15, v23
	s_waitcnt lgkmcnt(2)
	v_fmac_f32_e32 v39, v13, v24
	v_fmac_f32_e32 v39, v10, v25
	v_fmac_f32_e32 v39, v7, v26
	v_fmac_f32_e32 v39, v5, v27
	s_waitcnt lgkmcnt(1)
	v_fmac_f32_e32 v39, v4, v28
	v_fmac_f32_e32 v39, v3, v29
	v_fmac_f32_e32 v39, v14, v30
	v_fmac_f32_e32 v39, v11, v31
	s_waitcnt lgkmcnt(0)
	v_fmac_f32_e32 v39, v8, v32
	v_fmac_f32_e32 v39, v6, v33
	v_fmac_f32_e32 v39, v12, v34
	v_fmac_f32_e32 v39, v9, v35
	v_mul_f32_e64 v20, |v39|, s93
	v_exp_f32_e32 v20, v20
	v_sub_f32_e32 v21, v37, v38
	v_sub_f32_e32 v21, v36, v21
	v_mul_f32_e32 v21, 0x3d800000, v21
	v_add_f32_e32 v20, 1.0, v20
	v_cmp_gt_f32_e64 s[22:23], s94, v20
	s_nop 1
	v_cndmask_b32_e64 v22, 0, 32, s[22:23]
	v_ldexp_f32 v20, v20, v22
	v_log_f32_e32 v22, v20
	v_cndmask_b32_e64 v20, 0, v21, s[20:21]
	v_min_f32_e32 v21, 0, v39
	v_cndmask_b32_e64 v39, 0, v148, s[22:23]
	v_mul_f32_e32 v23, 0x3f317217, v22
	v_fma_f32 v23, v22, s95, -v23
	v_fmac_f32_e32 v23, 0x3377d1cf, v22
	v_fmac_f32_e32 v23, 0x3f317217, v22
	v_cmp_lt_f32_e64 s[24:25], |v22|, s96
	v_cmp_gt_u32_e64 s[22:23], s64, v99
	v_add_f32_e32 v20, v19, v20
	v_cndmask_b32_e64 v38, v22, v23, s[24:25]
	ds_read_b128 v[22:25], v122
	ds_read_b128 v[26:29], v122 offset:16
	ds_read_b128 v[30:33], v122 offset:32
	ds_read_b128 v[34:37], v122 offset:48
	s_waitcnt lgkmcnt(3)
	v_fma_f32 v22, v2, v22, v1
	v_fmac_f32_e32 v22, v0, v23
	v_fmac_f32_e32 v22, v16, v24
	v_fmac_f32_e32 v22, v15, v25
	s_waitcnt lgkmcnt(2)
	v_fmac_f32_e32 v22, v13, v26
	v_fmac_f32_e32 v22, v10, v27
	v_fmac_f32_e32 v22, v7, v28
	v_fmac_f32_e32 v22, v5, v29
	s_waitcnt lgkmcnt(1)
	v_fmac_f32_e32 v22, v4, v30
	v_fmac_f32_e32 v22, v3, v31
	v_fmac_f32_e32 v22, v14, v32
	v_fmac_f32_e32 v22, v11, v33
	s_waitcnt lgkmcnt(0)
	v_fmac_f32_e32 v22, v8, v34
	v_fmac_f32_e32 v22, v6, v35
	v_fmac_f32_e32 v22, v12, v36
	v_fmac_f32_e32 v22, v9, v37
	v_mul_f32_e64 v23, |v22|, s93
	v_exp_f32_e32 v23, v23
	v_sub_f32_e32 v24, v38, v39
	v_sub_f32_e32 v21, v21, v24
	v_min_f32_e32 v38, 0, v22
	v_add_f32_e32 v23, 1.0, v23
	v_cmp_gt_f32_e64 s[24:25], s94, v23
	v_mul_f32_e32 v21, 0x3d800000, v21
	v_cndmask_b32_e64 v21, 0, v21, s[22:23]
	v_cndmask_b32_e64 v24, 0, 32, s[24:25]
	v_ldexp_f32 v23, v23, v24
	v_log_f32_e32 v23, v23
	v_cndmask_b32_e64 v40, 0, v148, s[24:25]
	v_cmp_gt_u32_e64 s[24:25], s64, v100
	v_add_f32_e32 v21, v20, v21
	v_mul_f32_e32 v22, 0x3f317217, v23
	v_fma_f32 v22, v23, s95, -v22
	v_fmac_f32_e32 v22, 0x3377d1cf, v23
	v_fmac_f32_e32 v22, 0x3f317217, v23
	v_cmp_lt_f32_e64 s[26:27], |v23|, s96
	s_nop 1
	v_cndmask_b32_e64 v39, v23, v22, s[26:27]
	ds_read_b128 v[22:25], v123
	ds_read_b128 v[26:29], v123 offset:16
	ds_read_b128 v[30:33], v123 offset:32
	ds_read_b128 v[34:37], v123 offset:48
	s_waitcnt lgkmcnt(3)
	v_fma_f32 v41, v2, v22, v1
	v_fmac_f32_e32 v41, v0, v23
	v_fmac_f32_e32 v41, v16, v24
	v_fmac_f32_e32 v41, v15, v25
	s_waitcnt lgkmcnt(2)
	v_fmac_f32_e32 v41, v13, v26
	v_fmac_f32_e32 v41, v10, v27
	v_fmac_f32_e32 v41, v7, v28
	v_fmac_f32_e32 v41, v5, v29
	s_waitcnt lgkmcnt(1)
	v_fmac_f32_e32 v41, v4, v30
	v_fmac_f32_e32 v41, v3, v31
	v_fmac_f32_e32 v41, v14, v32
	v_fmac_f32_e32 v41, v11, v33
	s_waitcnt lgkmcnt(0)
	v_fmac_f32_e32 v41, v8, v34
	v_fmac_f32_e32 v41, v6, v35
	v_fmac_f32_e32 v41, v12, v36
	v_fmac_f32_e32 v41, v9, v37
	v_mul_f32_e64 v22, |v41|, s93
	v_exp_f32_e32 v22, v22
	v_sub_f32_e32 v23, v39, v40
	v_sub_f32_e32 v23, v38, v23
	v_mul_f32_e32 v23, 0x3d800000, v23
	v_add_f32_e32 v22, 1.0, v22
	v_cmp_gt_f32_e64 s[26:27], s94, v22
	s_nop 1
	v_cndmask_b32_e64 v24, 0, 32, s[26:27]
	v_ldexp_f32 v22, v22, v24
	v_log_f32_e32 v24, v22
	v_cndmask_b32_e64 v22, 0, v23, s[24:25]
	v_min_f32_e32 v23, 0, v41
	v_cndmask_b32_e64 v41, 0, v148, s[26:27]
	v_mul_f32_e32 v25, 0x3f317217, v24
	v_fma_f32 v25, v24, s95, -v25
	v_fmac_f32_e32 v25, 0x3377d1cf, v24
	v_fmac_f32_e32 v25, 0x3f317217, v24
	v_cmp_lt_f32_e64 s[28:29], |v24|, s96
	v_cmp_gt_u32_e64 s[26:27], s64, v101
	v_add_f32_e32 v22, v21, v22
	v_cndmask_b32_e64 v40, v24, v25, s[28:29]
	ds_read_b128 v[24:27], v124
	ds_read_b128 v[28:31], v124 offset:16
	ds_read_b128 v[32:35], v124 offset:32
	ds_read_b128 v[36:39], v124 offset:48
	s_waitcnt lgkmcnt(3)
	v_fma_f32 v24, v2, v24, v1
	v_fmac_f32_e32 v24, v0, v25
	v_fmac_f32_e32 v24, v16, v26
	v_fmac_f32_e32 v24, v15, v27
	s_waitcnt lgkmcnt(2)
; __device__ __forceinline__ void compute_b(const Params& P, const Item& I, unsigned char* lds) {
;     ...
;     float bl[16]; float run = 0.f;
; #pragma unroll
;     for (int i = 0; i < 16; ++i) { const int t = tq * 16 + i; float a = bias;
; #pragma unroll
;         for (int r = 0; r < 16; ++r) a += grs[t * 16 + r] * wc[r];
;         const float ls = fminf(a, 0.f) - __logf(1.0f + __expf(-fabsf(a)));
;         run += (t < I.L) ? ls * (1.0f / 16.0f) : 0.f; bl[i] = run; }
	v_fmac_f32_e32 v24, v13, v28
	v_fmac_f32_e32 v24, v10, v29
	v_fmac_f32_e32 v24, v7, v30
	v_fmac_f32_e32 v24, v5, v31
	s_waitcnt lgkmcnt(1)
	v_fmac_f32_e32 v24, v4, v32
	v_fmac_f32_e32 v24, v3, v33
	v_fmac_f32_e32 v24, v14, v34
	v_fmac_f32_e32 v24, v11, v35
	s_waitcnt lgkmcnt(0)
	v_fmac_f32_e32 v24, v8, v36
	v_fmac_f32_e32 v24, v6, v37
	v_fmac_f32_e32 v24, v12, v38
	v_fmac_f32_e32 v24, v9, v39
	v_mul_f32_e64 v25, |v24|, s93
	v_exp_f32_e32 v25, v25
	v_sub_f32_e32 v26, v40, v41
	v_sub_f32_e32 v23, v23, v26
	v_min_f32_e32 v40, 0, v24
	v_add_f32_e32 v25, 1.0, v25
	v_cmp_gt_f32_e64 s[28:29], s94, v25
	v_mul_f32_e32 v23, 0x3d800000, v23
	v_cndmask_b32_e64 v23, 0, v23, s[26:27]
	v_cndmask_b32_e64 v26, 0, 32, s[28:29]
	v_ldexp_f32 v25, v25, v26
	v_log_f32_e32 v25, v25
	v_cndmask_b32_e64 v42, 0, v148, s[28:29]
	v_cmp_gt_u32_e64 s[28:29], s64, v102
	v_add_f32_e32 v23, v22, v23
	v_mul_f32_e32 v24, 0x3f317217, v25
	v_fma_f32 v24, v25, s95, -v24
	v_fmac_f32_e32 v24, 0x3377d1cf, v25
	v_fmac_f32_e32 v24, 0x3f317217, v25
	v_cmp_lt_f32_e64 s[30:31], |v25|, s96
	s_nop 1
	v_cndmask_b32_e64 v41, v25, v24, s[30:31]
	ds_read_b128 v[24:27], v125
	ds_read_b128 v[28:31], v125 offset:16
	ds_read_b128 v[32:35], v125 offset:32
	ds_read_b128 v[36:39], v125 offset:48
	s_waitcnt lgkmcnt(3)
	v_fma_f32 v43, v2, v24, v1
	v_fmac_f32_e32 v43, v0, v25
	v_fmac_f32_e32 v43, v16, v26
	v_fmac_f32_e32 v43, v15, v27
	s_waitcnt lgkmcnt(2)
	v_fmac_f32_e32 v43, v13, v28
	v_fmac_f32_e32 v43, v10, v29
	v_fmac_f32_e32 v43, v7, v30
	v_fmac_f32_e32 v43, v5, v31
	s_waitcnt lgkmcnt(1)
	v_fmac_f32_e32 v43, v4, v32
	v_fmac_f32_e32 v43, v3, v33
	v_fmac_f32_e32 v43, v14, v34
	v_fmac_f32_e32 v43, v11, v35
	s_waitcnt lgkmcnt(0)
	v_fmac_f32_e32 v43, v8, v36
	v_fmac_f32_e32 v43, v6, v37
	v_fmac_f32_e32 v43, v12, v38
	v_fmac_f32_e32 v43, v9, v39
	v_mul_f32_e64 v24, |v43|, s93
	v_exp_f32_e32 v24, v24
	v_sub_f32_e32 v25, v41, v42
	v_sub_f32_e32 v25, v40, v25
	v_mul_f32_e32 v25, 0x3d800000, v25
	v_add_f32_e32 v24, 1.0, v24
	v_cmp_gt_f32_e64 s[30:31], s94, v24
	s_nop 1
	v_cndmask_b32_e64 v26, 0, 32, s[30:31]
	v_ldexp_f32 v24, v24, v26
	v_log_f32_e32 v26, v24
	v_cndmask_b32_e64 v24, 0, v25, s[28:29]
	v_min_f32_e32 v25, 0, v43
	v_cndmask_b32_e64 v43, 0, v148, s[30:31]
	v_mul_f32_e32 v27, 0x3f317217, v26
	v_fma_f32 v27, v26, s95, -v27
	v_fmac_f32_e32 v27, 0x3377d1cf, v26
	v_fmac_f32_e32 v27, 0x3f317217, v26
	v_cmp_lt_f32_e64 s[34:35], |v26|, s96
	v_cmp_gt_u32_e64 s[30:31], s64, v103
	v_add_f32_e32 v24, v23, v24
	v_cndmask_b32_e64 v42, v26, v27, s[34:35]
	ds_read_b128 v[26:29], v126
	ds_read_b128 v[30:33], v126 offset:16
	ds_read_b128 v[34:37], v126 offset:32
	ds_read_b128 v[38:41], v126 offset:48
	s_waitcnt lgkmcnt(3)
	v_fma_f32 v26, v2, v26, v1
	v_fmac_f32_e32 v26, v0, v27
	v_fmac_f32_e32 v26, v16, v28
	v_fmac_f32_e32 v26, v15, v29
	s_waitcnt lgkmcnt(2)
	v_fmac_f32_e32 v26, v13, v30
	v_fmac_f32_e32 v26, v10, v31
	v_fmac_f32_e32 v26, v7, v32
	v_fmac_f32_e32 v26, v5, v33
	s_waitcnt lgkmcnt(1)
	v_fmac_f32_e32 v26, v4, v34
	v_fmac_f32_e32 v26, v3, v35
	v_fmac_f32_e32 v26, v14, v36
	v_fmac_f32_e32 v26, v11, v37
	s_waitcnt lgkmcnt(0)
	v_fmac_f32_e32 v26, v8, v38
	v_fmac_f32_e32 v26, v6, v39
	v_fmac_f32_e32 v26, v12, v40
	v_fmac_f32_e32 v26, v9, v41
	v_mul_f32_e64 v27, |v26|, s93
	v_exp_f32_e32 v27, v27
	v_sub_f32_e32 v28, v42, v43
	v_sub_f32_e32 v25, v25, v28
	v_min_f32_e32 v42, 0, v26
	v_add_f32_e32 v27, 1.0, v27
	v_cmp_gt_f32_e64 s[34:35], s94, v27
	v_mul_f32_e32 v25, 0x3d800000, v25
	v_cndmask_b32_e64 v25, 0, v25, s[30:31]
	v_cndmask_b32_e64 v28, 0, 32, s[34:35]
	v_ldexp_f32 v27, v27, v28
	v_log_f32_e32 v27, v27
	v_cndmask_b32_e64 v44, 0, v148, s[34:35]
	v_cmp_gt_u32_e64 s[34:35], s64, v104
	v_add_f32_e32 v25, v24, v25
	v_mul_f32_e32 v26, 0x3f317217, v27
	v_fma_f32 v26, v27, s95, -v26
	v_fmac_f32_e32 v26, 0x3377d1cf, v27
	v_fmac_f32_e32 v26, 0x3f317217, v27
	v_cmp_lt_f32_e64 s[36:37], |v27|, s96
	s_nop 1
	v_cndmask_b32_e64 v43, v27, v26, s[36:37]
	ds_read_b128 v[26:29], v127
	ds_read_b128 v[30:33], v127 offset:16
	ds_read_b128 v[34:37], v127 offset:32
	ds_read_b128 v[38:41], v127 offset:48
	s_waitcnt lgkmcnt(3)
	v_fma_f32 v45, v2, v26, v1
	v_fmac_f32_e32 v45, v0, v27
	v_fmac_f32_e32 v45, v16, v28
	v_fmac_f32_e32 v45, v15, v29
	s_waitcnt lgkmcnt(2)
	v_fmac_f32_e32 v45, v13, v30
	v_fmac_f32_e32 v45, v10, v31
	v_fmac_f32_e32 v45, v7, v32
	v_fmac_f32_e32 v45, v5, v33
	s_waitcnt lgkmcnt(1)
	v_fmac_f32_e32 v45, v4, v34
	v_fmac_f32_e32 v45, v3, v35
	v_fmac_f32_e32 v45, v14, v36
	v_fmac_f32_e32 v45, v11, v37
	s_waitcnt lgkmcnt(0)
	v_fmac_f32_e32 v45, v8, v38
	v_fmac_f32_e32 v45, v6, v39
	v_fmac_f32_e32 v45, v12, v40
	v_fmac_f32_e32 v45, v9, v41
	v_mul_f32_e64 v26, |v45|, s93
	v_exp_f32_e32 v26, v26
	v_sub_f32_e32 v27, v43, v44
	v_sub_f32_e32 v27, v42, v27
	v_mul_f32_e32 v27, 0x3d800000, v27
	v_add_f32_e32 v26, 1.0, v26
	v_cmp_gt_f32_e64 s[36:37], s94, v26
	s_nop 1
	v_cndmask_b32_e64 v28, 0, 32, s[36:37]
	v_ldexp_f32 v26, v26, v28
	v_log_f32_e32 v28, v26
	v_cndmask_b32_e64 v26, 0, v27, s[34:35]
	v_min_f32_e32 v27, 0, v45
	v_cndmask_b32_e64 v45, 0, v148, s[36:37]
	v_mul_f32_e32 v29, 0x3f317217, v28
	v_fma_f32 v29, v28, s95, -v29
	v_fmac_f32_e32 v29, 0x3377d1cf, v28
	v_fmac_f32_e32 v29, 0x3f317217, v28
	v_cmp_lt_f32_e64 s[38:39], |v28|, s96
	v_cmp_gt_u32_e64 s[36:37], s64, v105
	v_add_f32_e32 v26, v25, v26
	v_cndmask_b32_e64 v44, v28, v29, s[38:39]
	ds_read_b128 v[28:31], v128
	ds_read_b128 v[32:35], v128 offset:16
	ds_read_b128 v[36:39], v128 offset:32
	ds_read_b128 v[40:43], v128 offset:48
	s_waitcnt lgkmcnt(3)
	v_fma_f32 v28, v2, v28, v1
	v_fmac_f32_e32 v28, v0, v29
	v_fmac_f32_e32 v28, v16, v30
	v_fmac_f32_e32 v28, v15, v31
	s_waitcnt lgkmcnt(2)
; __device__ __forceinline__ void compute_b(const Params& P, const Item& I, unsigned char* lds) {
;     ...
;     float bl[16]; float run = 0.f;
; #pragma unroll
;     for (int i = 0; i < 16; ++i) { const int t = tq * 16 + i; float a = bias;
; #pragma unroll
;         for (int r = 0; r < 16; ++r) a += grs[t * 16 + r] * wc[r];
;         const float ls = fminf(a, 0.f) - __logf(1.0f + __expf(-fabsf(a)));
;         run += (t < I.L) ? ls * (1.0f / 16.0f) : 0.f; bl[i] = run; }
;     qt[tq * 128 + dk] = run;
;     __syncthreads();
	v_fmac_f32_e32 v28, v13, v32
	v_fmac_f32_e32 v28, v10, v33
	v_fmac_f32_e32 v28, v7, v34
	v_fmac_f32_e32 v28, v5, v35
	s_waitcnt lgkmcnt(1)
	v_fmac_f32_e32 v28, v4, v36
	v_fmac_f32_e32 v28, v3, v37
	v_fmac_f32_e32 v28, v14, v38
	v_fmac_f32_e32 v28, v11, v39
	s_waitcnt lgkmcnt(0)
	v_fmac_f32_e32 v28, v8, v40
	v_fmac_f32_e32 v28, v6, v41
	v_fmac_f32_e32 v28, v12, v42
	v_fmac_f32_e32 v28, v9, v43
	v_mul_f32_e64 v29, |v28|, s93
	v_exp_f32_e32 v29, v29
	v_sub_f32_e32 v30, v44, v45
	v_sub_f32_e32 v27, v27, v30
	v_min_f32_e32 v44, 0, v28
	v_add_f32_e32 v29, 1.0, v29
	v_cmp_gt_f32_e64 s[38:39], s94, v29
	v_mul_f32_e32 v27, 0x3d800000, v27
	v_cndmask_b32_e64 v27, 0, v27, s[36:37]
	v_cndmask_b32_e64 v30, 0, 32, s[38:39]
	v_ldexp_f32 v29, v29, v30
	v_log_f32_e32 v29, v29
	v_cndmask_b32_e64 v46, 0, v148, s[38:39]
	v_cmp_gt_u32_e64 s[38:39], s64, v106
	v_add_f32_e32 v27, v26, v27
	v_mul_f32_e32 v28, 0x3f317217, v29
	v_fma_f32 v28, v29, s95, -v28
	v_fmac_f32_e32 v28, 0x3377d1cf, v29
	v_fmac_f32_e32 v28, 0x3f317217, v29
	v_cmp_lt_f32_e64 s[40:41], |v29|, s96
	s_nop 1
	v_cndmask_b32_e64 v45, v29, v28, s[40:41]
	ds_read_b128 v[28:31], v129
	ds_read_b128 v[32:35], v129 offset:16
	ds_read_b128 v[36:39], v129 offset:32
	ds_read_b128 v[40:43], v129 offset:48
	s_waitcnt lgkmcnt(3)
	v_fma_f32 v47, v2, v28, v1
	v_fmac_f32_e32 v47, v0, v29
	v_fmac_f32_e32 v47, v16, v30
	v_fmac_f32_e32 v47, v15, v31
	s_waitcnt lgkmcnt(2)
	v_fmac_f32_e32 v47, v13, v32
	v_fmac_f32_e32 v47, v10, v33
	v_fmac_f32_e32 v47, v7, v34
	v_fmac_f32_e32 v47, v5, v35
	s_waitcnt lgkmcnt(1)
	v_fmac_f32_e32 v47, v4, v36
	v_fmac_f32_e32 v47, v3, v37
	v_fmac_f32_e32 v47, v14, v38
	v_fmac_f32_e32 v47, v11, v39
	s_waitcnt lgkmcnt(0)
	v_fmac_f32_e32 v47, v8, v40
	v_fmac_f32_e32 v47, v6, v41
	v_fmac_f32_e32 v47, v12, v42
	v_fmac_f32_e32 v47, v9, v43
	v_mul_f32_e64 v28, |v47|, s93
	v_exp_f32_e32 v28, v28
	v_sub_f32_e32 v29, v45, v46
	v_sub_f32_e32 v29, v44, v29
	v_mul_f32_e32 v29, 0x3d800000, v29
	v_add_f32_e32 v28, 1.0, v28
	v_cmp_gt_f32_e64 s[40:41], s94, v28
	s_nop 1
	v_cndmask_b32_e64 v30, 0, 32, s[40:41]
	v_ldexp_f32 v28, v28, v30
	v_log_f32_e32 v30, v28
	v_cndmask_b32_e64 v28, 0, v29, s[38:39]
	v_min_f32_e32 v29, 0, v47
	v_cndmask_b32_e64 v47, 0, v148, s[40:41]
	v_mul_f32_e32 v31, 0x3f317217, v30
	v_fma_f32 v31, v30, s95, -v31
	v_fmac_f32_e32 v31, 0x3377d1cf, v30
	v_fmac_f32_e32 v31, 0x3f317217, v30
	v_cmp_lt_f32_e64 s[42:43], |v30|, s96
	v_cmp_gt_u32_e64 s[40:41], s64, v107
	v_add_f32_e32 v28, v27, v28
	v_cndmask_b32_e64 v46, v30, v31, s[42:43]
	ds_read_b128 v[30:33], v130
	ds_read_b128 v[34:37], v130 offset:16
	ds_read_b128 v[38:41], v130 offset:32
	ds_read_b128 v[42:45], v130 offset:48
	s_waitcnt lgkmcnt(3)
	v_fma_f32 v30, v2, v30, v1
	v_fmac_f32_e32 v30, v0, v31
	v_fmac_f32_e32 v30, v16, v32
	v_fmac_f32_e32 v30, v15, v33
	s_waitcnt lgkmcnt(2)
	v_fmac_f32_e32 v30, v13, v34
	v_fmac_f32_e32 v30, v10, v35
	v_fmac_f32_e32 v30, v7, v36
	v_fmac_f32_e32 v30, v5, v37
	s_waitcnt lgkmcnt(1)
	v_fmac_f32_e32 v30, v4, v38
	v_fmac_f32_e32 v30, v3, v39
	v_fmac_f32_e32 v30, v14, v40
	v_fmac_f32_e32 v30, v11, v41
	s_waitcnt lgkmcnt(0)
	v_fmac_f32_e32 v30, v8, v42
	v_fmac_f32_e32 v30, v6, v43
	v_fmac_f32_e32 v30, v12, v44
	v_fmac_f32_e32 v30, v9, v45
	v_mul_f32_e64 v31, |v30|, s93
	v_exp_f32_e32 v31, v31
	v_sub_f32_e32 v32, v46, v47
	v_sub_f32_e32 v29, v29, v32
	v_min_f32_e32 v46, 0, v30
	v_add_f32_e32 v31, 1.0, v31
	v_cmp_gt_f32_e64 s[42:43], s94, v31
	v_mul_f32_e32 v29, 0x3d800000, v29
	v_cndmask_b32_e64 v29, 0, v29, s[40:41]
	v_cndmask_b32_e64 v32, 0, 32, s[42:43]
	v_ldexp_f32 v31, v31, v32
	v_log_f32_e32 v31, v31
	v_cndmask_b32_e64 v48, 0, v148, s[42:43]
	v_cmp_gt_u32_e64 s[42:43], s64, v108
	v_add_f32_e32 v29, v28, v29
	v_mul_f32_e32 v30, 0x3f317217, v31
	v_fma_f32 v30, v31, s95, -v30
	v_fmac_f32_e32 v30, 0x3377d1cf, v31
	v_fmac_f32_e32 v30, 0x3f317217, v31
	v_cmp_lt_f32_e64 s[44:45], |v31|, s96
	s_nop 1
	v_cndmask_b32_e64 v47, v31, v30, s[44:45]
	ds_read_b128 v[30:33], v131
	ds_read_b128 v[34:37], v131 offset:16
	ds_read_b128 v[38:41], v131 offset:32
	ds_read_b128 v[42:45], v131 offset:48
	s_waitcnt lgkmcnt(3)
	v_fma_f32 v49, v2, v30, v1
	v_fmac_f32_e32 v49, v0, v31
	v_fmac_f32_e32 v49, v16, v32
	v_fmac_f32_e32 v49, v15, v33
	s_waitcnt lgkmcnt(2)
	v_fmac_f32_e32 v49, v13, v34
	v_fmac_f32_e32 v49, v10, v35
	v_fmac_f32_e32 v49, v7, v36
	v_fmac_f32_e32 v49, v5, v37
	s_waitcnt lgkmcnt(1)
	v_fmac_f32_e32 v49, v4, v38
	v_fmac_f32_e32 v49, v3, v39
	v_fmac_f32_e32 v49, v14, v40
	v_fmac_f32_e32 v49, v11, v41
	s_waitcnt lgkmcnt(0)
	v_fmac_f32_e32 v49, v8, v42
	v_fmac_f32_e32 v49, v6, v43
	v_fmac_f32_e32 v49, v12, v44
	v_fmac_f32_e32 v49, v9, v45
	v_mul_f32_e64 v30, |v49|, s93
	v_exp_f32_e32 v30, v30
	v_sub_f32_e32 v31, v47, v48
	v_sub_f32_e32 v31, v46, v31
	v_mul_f32_e32 v31, 0x3d800000, v31
	v_add_f32_e32 v30, 1.0, v30
	v_cmp_gt_f32_e64 s[44:45], s94, v30
	s_nop 1
	v_cndmask_b32_e64 v32, 0, 32, s[44:45]
	v_ldexp_f32 v30, v30, v32
	v_log_f32_e32 v32, v30
	v_cndmask_b32_e64 v30, 0, v31, s[42:43]
	v_min_f32_e32 v31, 0, v49
	v_cndmask_b32_e64 v49, 0, v148, s[44:45]
	v_mul_f32_e32 v33, 0x3f317217, v32
	v_fma_f32 v33, v32, s95, -v33
	v_fmac_f32_e32 v33, 0x3377d1cf, v32
	v_fmac_f32_e32 v33, 0x3f317217, v32
	v_cmp_lt_f32_e64 s[46:47], |v32|, s96
	v_cmp_gt_u32_e64 s[44:45], s64, v109
	v_add_f32_e32 v30, v29, v30
	v_cndmask_b32_e64 v48, v32, v33, s[46:47]
	ds_read_b128 v[32:35], v132
	ds_read_b128 v[36:39], v132 offset:16
	ds_read_b128 v[40:43], v132 offset:32
	ds_read_b128 v[44:47], v132 offset:48
	s_waitcnt lgkmcnt(3)
	v_fmac_f32_e32 v1, v2, v32
	v_fmac_f32_e32 v1, v0, v33
	v_fmac_f32_e32 v1, v16, v34
	v_fmac_f32_e32 v1, v15, v35
	s_waitcnt lgkmcnt(2)
	v_fmac_f32_e32 v1, v13, v36
	v_fmac_f32_e32 v1, v10, v37
	v_fmac_f32_e32 v1, v7, v38
	v_fmac_f32_e32 v1, v5, v39
	s_waitcnt lgkmcnt(1)
	v_fmac_f32_e32 v1, v4, v40
	v_fmac_f32_e32 v1, v3, v41
	v_fmac_f32_e32 v1, v14, v42
	v_fmac_f32_e32 v1, v11, v43
	s_waitcnt lgkmcnt(0)
	v_fmac_f32_e32 v1, v8, v44
	v_fmac_f32_e32 v1, v6, v45
	v_fmac_f32_e32 v1, v12, v46
	v_fmac_f32_e32 v1, v9, v47
	v_mul_f32_e64 v0, |v1|, s93
	v_exp_f32_e32 v0, v0
	v_sub_f32_e32 v2, v48, v49
	v_sub_f32_e32 v2, v31, v2
	v_mul_f32_e32 v2, 0x3d800000, v2
	v_add_f32_e32 v0, 1.0, v0
	v_cmp_gt_f32_e64 s[46:47], s94, v0
	v_min_f32_e32 v1, 0, v1
	s_nop 0
	v_cndmask_b32_e64 v3, 0, 32, s[46:47]
	v_ldexp_f32 v0, v0, v3
	v_log_f32_e32 v3, v0
	v_cndmask_b32_e64 v0, 0, v2, s[44:45]
	v_add_f32_e32 v0, v30, v0
	v_mul_f32_e32 v2, 0x3f317217, v3
	v_fma_f32 v2, v3, s95, -v2
	v_fmac_f32_e32 v2, 0x3377d1cf, v3
	v_fmac_f32_e32 v2, 0x3f317217, v3
	v_cmp_lt_f32_e64 s[48:49], |v3|, s96
	s_nop 1
	v_cndmask_b32_e64 v2, v3, v2, s[48:49]
	v_cndmask_b32_e64 v3, 0, v148, s[46:47]
	v_sub_f32_e32 v2, v2, v3
	v_sub_f32_e32 v1, v1, v2
	v_mul_f32_e32 v1, 0x3d800000, v1
	v_cmp_gt_u32_e64 s[46:47], s64, v110
	v_mov_b32_e32 v2, 0
	s_nop 0
	v_cndmask_b32_e64 v1, 0, v1, s[46:47]
	v_add_f32_e32 v1, v0, v1
	ds_write_b32 v111, v1 offset:36864
	s_waitcnt lgkmcnt(0)
	s_barrier
; __device__ __forceinline__ void compute_b(const Params& P, const Item& I, unsigned char* lds) {
;     ...
;     float off = 0.f;
; #pragma unroll
;     for (int q = 0; q < 3; ++q) if (q < tq) off += qt[q * 128 + dk];
	s_and_saveexec_b64 s[48:49], s[10:11]
	s_cbranch_execz .LBB0_1976
	ds_read_b32 v2, v112 offset:36864
	s_waitcnt lgkmcnt(0)
	v_add_f32_e32 v2, 0, v2
	s_or_b64 exec, exec, s[48:49]
	s_and_saveexec_b64 s[48:49], s[12:13]
	s_cbranch_execnz .LBB0_1977

; __device__ __forceinline__ unsigned cvt_pk_bf16(float lo, float hi) { unsigned r; asm volatile("v_cvt_pk_bf16_f32 %0, %1, %2" : "=v"(r) : "v"(lo), "v"(hi)); return r; }
; __device__ __forceinline__ float bf1(bf16_t b) { return __uint_as_float(((unsigned)b) << 16); }
; __device__ __forceinline__ Item decode_item(int it) { Item I; if (it < 1024) { const int b = it >> 8; I.h = (it >> 6) & 3; I.row0 = b * SEQ + (it & 63) * 64; I.L = 64; } else { const int j = it - 1024; I.h = j & 3; I.row0 = MP_ROWS + (j >> 2) * 16; I.L = 16; } I.j = it; return I; }
; __device__ __forceinline__ void compute_b(const Params& P, const Item& I, unsigned char* lds) {
;     ...
; #pragma unroll
;     for (int i = 0; i < 16; ++i) bsh[(tq * 16 + i) * 128 + dk] = bl[i] + off;
;     __syncthreads();
; }
; __device__ __forceinline__ void gla_g1(const Params& P, unsigned char* lds) {
;     const int tid = threadIdx.x, wid = tid >> 6, lane = tid & 63, fr = lane & 15, fq = lane >> 4;
;     const bf16_t* kg = (const bf16_t*)(P.ws + O_K); const bf16_t* vT = (const bf16_t*)(P.ws + O_VT);
;     bf16_t* KVT = (bf16_t*)(P.ws + O_KVT); float* dec = (float*)(P.ws + O_DEC);
;     const float* bsh = (const float*)(lds + L_BSH); bf16_t* kT = (bf16_t*)(lds + L_KT);
;     for (int it = blockIdx.x; it < NITEM; it += gridDim.x) {
;         const Item I = decode_item(it);
;         compute_b(P, I, lds);
;         { const int dk = tid & 127, tq = tid >> 7; const float blast = bsh[63 * 128 + dk]; float ke[16];
;             bf16_t kraw[16];
; #pragma unroll
;             for (int i = 0; i < 16; ++i) { const int t = tq * 16 + i, tc = t < I.L ? t : I.L - 1; kraw[i] = kg[(size_t)(I.row0 + tc) * KEYD + I.h * DK + dk]; }
; #pragma unroll
;             for (int i = 0; i < 16; ++i) { const int t = tq * 16 + i; const float kv = bf1(kraw[i]) * __expf(blast - bsh[t * 128 + dk]); ke[i] = t < I.L ? kv : 0.f; }
;             u32x4 w0, w1; w0.x = cvt_pk_bf16(ke[0], ke[1]); w0.y = cvt_pk_bf16(ke[2], ke[3]); w0.z = cvt_pk_bf16(ke[4], ke[5]); w0.w = cvt_pk_bf16(ke[6], ke[7]);
;             w1.x = cvt_pk_bf16(ke[8], ke[9]); w1.y = cvt_pk_bf16(ke[10], ke[11]); w1.z = cvt_pk_bf16(ke[12], ke[13]); w1.w = cvt_pk_bf16(ke[14], ke[15]);
;             *(u32x4*)(kT + dk * 72 + tq * 16) = w0; *(u32x4*)(kT + dk * 72 + tq * 16 + 8) = w1;
.LBB0_1970:
	s_or_b64 exec, exec, s[48:49]
	v_add_f32_e32 v3, v17, v2
	v_add_f32_e32 v4, v18, v2
	ds_write2st64_b32 v113, v3, v4 offset0:16 offset1:18
	v_add_f32_e32 v3, v19, v2
	v_add_f32_e32 v4, v20, v2
	ds_write2st64_b32 v113, v3, v4 offset0:20 offset1:22
	v_add_f32_e32 v3, v21, v2
	v_add_f32_e32 v4, v22, v2
	ds_write2st64_b32 v113, v3, v4 offset0:24 offset1:26
	v_add_f32_e32 v3, v23, v2
	v_add_f32_e32 v4, v24, v2
	ds_write2st64_b32 v113, v3, v4 offset0:28 offset1:30
	v_add_f32_e32 v3, v25, v2
	v_add_f32_e32 v4, v26, v2
	ds_write2st64_b32 v113, v3, v4 offset0:32 offset1:34
	v_add_f32_e32 v3, v27, v2
	v_add_f32_e32 v4, v28, v2
	s_add_i32 s48, s64, -1
	ds_write2st64_b32 v113, v3, v4 offset0:36 offset1:38
	v_add_f32_e32 v3, v29, v2
	v_add_f32_e32 v4, v30, v2
	v_add_f32_e32 v0, v0, v2
	v_add_f32_e32 v1, v1, v2
	v_min_i32_e32 v2, s48, v95
	ds_write2st64_b32 v113, v3, v4 offset0:40 offset1:42
	v_add_u32_e32 v2, s82, v2
	v_min_i32_e32 v4, s48, v96
	s_lshl_b32 s76, s76, 1
	v_ashrrev_i32_e32 v3, 31, v2
	v_add_u32_e32 v4, s82, v4
	ds_write2st64_b32 v113, v0, v1 offset0:44 offset1:46
	v_lshl_add_u64 v[0:1], v[66:67], 0, s[76:77]
	v_lshlrev_b64 v[2:3], 10, v[2:3]
	v_ashrrev_i32_e32 v5, 31, v4
	v_lshl_add_u64 v[2:3], v[0:1], 0, v[2:3]
	v_lshlrev_b64 v[4:5], 10, v[4:5]
	s_waitcnt lgkmcnt(0)
	s_barrier
	v_lshl_add_u64 v[4:5], v[0:1], 0, v[4:5]
	s_waitcnt vmcnt(4)
	v_mov_b32_e32 v18, v212
	v_mov_b32_e32 v19, v213
	v_min_i32_e32 v6, s48, v97
	v_min_i32_e32 v10, s48, v101
	v_add_u32_e32 v6, s82, v6
	v_add_u32_e32 v10, s82, v10
	v_ashrrev_i32_e32 v7, 31, v6
	v_ashrrev_i32_e32 v11, 31, v10
	v_lshlrev_b64 v[6:7], 10, v[6:7]
	v_lshlrev_b64 v[10:11], 10, v[10:11]
	v_min_i32_e32 v12, s48, v102
	v_lshl_add_u64 v[6:7], v[0:1], 0, v[6:7]
	v_min_i32_e32 v8, s48, v98
	v_lshl_add_u64 v[10:11], v[0:1], 0, v[10:11]
	v_add_u32_e32 v12, s82, v12
	v_ashrrev_i32_e32 v13, 31, v12
	v_mov_b32_e32 v20, v214
	v_mov_b32_e32 v24, v218
	v_add_u32_e32 v2, s82, v8
	v_min_i32_e32 v4, s48, v99
	v_min_i32_e32 v8, s48, v100
	v_add_u32_e32 v4, s82, v4
	v_add_u32_e32 v8, s82, v8
	v_lshlrev_b64 v[6:7], 10, v[12:13]
	v_min_i32_e32 v12, s48, v103
	v_ashrrev_i32_e32 v3, 31, v2
	v_ashrrev_i32_e32 v5, 31, v4
	v_ashrrev_i32_e32 v9, 31, v8
	v_add_u32_e32 v12, s82, v12
	v_lshlrev_b64 v[2:3], 10, v[2:3]
	v_lshlrev_b64 v[4:5], 10, v[4:5]
	v_lshlrev_b64 v[8:9], 10, v[8:9]
	v_ashrrev_i32_e32 v13, 31, v12
	v_lshl_add_u64 v[2:3], v[0:1], 0, v[2:3]
	v_lshl_add_u64 v[4:5], v[0:1], 0, v[4:5]
	v_lshl_add_u64 v[8:9], v[0:1], 0, v[8:9]
	v_lshlrev_b64 v[12:13], 10, v[12:13]
	v_mov_b32_e32 v21, v215
	v_mov_b32_e32 v22, v216
	v_mov_b32_e32 v23, v217
	v_lshl_add_u64 v[2:3], v[0:1], 0, v[12:13]
	v_min_i32_e32 v12, s48, v104
	v_add_u32_e32 v4, s82, v12
	v_min_i32_e32 v12, s48, v105
	v_add_u32_e32 v12, s82, v12
	v_ashrrev_i32_e32 v13, 31, v12
	v_lshlrev_b64 v[12:13], 10, v[12:13]
	v_lshl_add_u64 v[8:9], v[0:1], 0, v[12:13]
	v_min_i32_e32 v12, s48, v106
	v_add_u32_e32 v10, s82, v12
	v_min_i32_e32 v12, s48, v107
	v_add_u32_e32 v12, s82, v12
	v_ashrrev_i32_e32 v13, 31, v12
	v_lshl_add_u64 v[6:7], v[0:1], 0, v[6:7]
	v_lshlrev_b64 v[12:13], 10, v[12:13]
	v_mov_b32_e32 v25, v219
	v_mov_b32_e32 v26, v220
	v_lshl_add_u64 v[6:7], v[0:1], 0, v[12:13]
	v_min_i32_e32 v12, s48, v108
	v_add_u32_e32 v2, s82, v12
	v_ashrrev_i32_e32 v3, 31, v2
	v_lshlrev_b64 v[2:3], 10, v[2:3]
	v_ashrrev_i32_e32 v5, 31, v4
	v_lshl_add_u64 v[12:13], v[0:1], 0, v[2:3]
	v_min_i32_e32 v2, s48, v109
	v_lshlrev_b64 v[4:5], 10, v[4:5]
	v_add_u32_e32 v2, s82, v2
	v_lshl_add_u64 v[4:5], v[0:1], 0, v[4:5]
	v_ashrrev_i32_e32 v3, 31, v2
	v_lshlrev_b64 v[14:15], 10, v[2:3]
	ds_read_b32 v2, v114 offset:4096
	ds_read_b32 v3, v113 offset:4096
	v_mov_b32_e32 v27, v221
	v_min_i32_e32 v16, s48, v110
	v_ashrrev_i32_e32 v11, 31, v10
	v_add_u32_e32 v16, s82, v16
	v_lshlrev_b64 v[10:11], 10, v[10:11]
	v_ashrrev_i32_e32 v17, 31, v16
	v_lshl_add_u64 v[10:11], v[0:1], 0, v[10:11]
	v_mov_b32_e32 v8, v222
	v_lshlrev_b64 v[4:5], 10, v[16:17]
	v_lshl_add_u64 v[14:15], v[0:1], 0, v[14:15]
	v_lshl_add_u64 v[0:1], v[0:1], 0, v[4:5]
	v_mov_b32_e32 v5, v223
	s_nop 0
	v_mov_b32_e32 v6, v224
	s_waitcnt lgkmcnt(0)
	v_sub_f32_e32 v3, v2, v3
	v_mul_f32_e32 v3, 0x3fb8aa3b, v3
	v_exp_f32_e32 v3, v3
	v_lshlrev_b32_e32 v4, 16, v18
	v_mul_f32_e32 v3, v3, v4
	v_lshlrev_b32_e32 v4, 16, v19
	ds_read_b32 v7, v133 offset:4096
	ds_read_b32 v9, v134 offset:4096
	ds_read_b32 v10, v135 offset:4096
	ds_read_b32 v11, v136 offset:4096
	ds_read_b32 v16, v137 offset:4096
	ds_read_b32 v17, v138 offset:4096
	ds_read_b32 v18, v139 offset:4096
	ds_read_b32 v19, v140 offset:4096
	v_mov_b32_e32 v12, v225
	s_waitcnt lgkmcnt(7)
	v_sub_f32_e32 v7, v2, v7
	v_mov_b32_e32 v0, v227
	v_mul_f32_e32 v7, 0x3fb8aa3b, v7
	v_mov_b32_e32 v13, v226
	s_waitcnt lgkmcnt(6)
	v_sub_f32_e32 v9, v2, v9
	v_exp_f32_e32 v7, v7
	v_mul_f32_e32 v9, 0x3fb8aa3b, v9
	v_exp_f32_e32 v9, v9
	s_waitcnt lgkmcnt(2)
	v_sub_f32_e32 v14, v2, v17
	v_mul_f32_e32 v4, v7, v4
	v_lshlrev_b32_e32 v7, 16, v20
	v_mul_f32_e32 v7, v9, v7
	v_sub_f32_e32 v9, v2, v10
	v_mul_f32_e32 v9, 0x3fb8aa3b, v9
	v_sub_f32_e32 v10, v2, v11
	v_exp_f32_e32 v9, v9
	v_mul_f32_e32 v10, 0x3fb8aa3b, v10
	v_exp_f32_e32 v10, v10
	v_sub_f32_e32 v11, v2, v16
	v_mul_f32_e32 v11, 0x3fb8aa3b, v11
	v_exp_f32_e32 v11, v11
	v_mul_f32_e32 v14, 0x3fb8aa3b, v14
	s_waitcnt lgkmcnt(1)
	v_sub_f32_e32 v15, v2, v18
	v_exp_f32_e32 v14, v14
	v_lshlrev_b32_e32 v1, 16, v21
	v_mul_f32_e32 v1, v9, v1
	v_lshlrev_b32_e32 v9, 16, v22
	v_mul_f32_e32 v9, v10, v9
	v_lshlrev_b32_e32 v10, 16, v23
	v_mul_f32_e32 v15, 0x3fb8aa3b, v15
	s_waitcnt lgkmcnt(0)
; __device__ __forceinline__ unsigned cvt_pk_bf16(float lo, float hi) { unsigned r; asm volatile("v_cvt_pk_bf16_f32 %0, %1, %2" : "=v"(r) : "v"(lo), "v"(hi)); return r; }
; __device__ __forceinline__ float bf1(bf16_t b) { return __uint_as_float(((unsigned)b) << 16); }
; __device__ __forceinline__ void gla_g1(const Params& P, unsigned char* lds) {
;     ...
;             for (int i = 0; i < 16; ++i) { const int t = tq * 16 + i, tc = t < I.L ? t : I.L - 1; kraw[i] = kg[(size_t)(I.row0 + tc) * KEYD + I.h * DK + dk]; }
; #pragma unroll
;             for (int i = 0; i < 16; ++i) { const int t = tq * 16 + i; const float kv = bf1(kraw[i]) * __expf(blast - bsh[t * 128 + dk]); ke[i] = t < I.L ? kv : 0.f; }
;             u32x4 w0, w1; w0.x = cvt_pk_bf16(ke[0], ke[1]); w0.y = cvt_pk_bf16(ke[2], ke[3]); w0.z = cvt_pk_bf16(ke[4], ke[5]); w0.w = cvt_pk_bf16(ke[6], ke[7]);
;             w1.x = cvt_pk_bf16(ke[8], ke[9]); w1.y = cvt_pk_bf16(ke[10], ke[11]); w1.z = cvt_pk_bf16(ke[12], ke[13]); w1.w = cvt_pk_bf16(ke[14], ke[15]);
;             *(u32x4*)(kT + dk * 72 + tq * 16) = w0; *(u32x4*)(kT + dk * 72 + tq * 16 + 8) = w1;
;             if (tq == 0) dec[(size_t)it * 128 + dk] = __expf(blast); }
	v_sub_f32_e32 v16, v2, v19
	ds_read_b32 v17, v141 offset:4096
	ds_read_b32 v18, v142 offset:4096
	ds_read_b32 v19, v143 offset:4096
	ds_read_b32 v20, v144 offset:4096
	ds_read_b32 v21, v145 offset:4096
	ds_read_b32 v22, v146 offset:4096
	ds_read_b32 v23, v147 offset:4096
	v_exp_f32_e32 v15, v15
	v_mul_f32_e32 v16, 0x3fb8aa3b, v16
	s_waitcnt lgkmcnt(6)
	v_sub_f32_e32 v17, v2, v17
	v_exp_f32_e32 v16, v16
	v_mul_f32_e32 v17, 0x3fb8aa3b, v17
	v_mul_f32_e32 v10, v11, v10
	v_lshlrev_b32_e32 v11, 16, v24
	v_exp_f32_e32 v17, v17
	v_mul_f32_e32 v11, v14, v11
	v_cndmask_b32_e64 v4, 0, v4, s[16:17]
	v_lshlrev_b32_e32 v14, 16, v25
	v_mul_f32_e32 v14, v15, v14
	v_lshlrev_b32_e32 v15, 16, v26
	v_mul_f32_e32 v15, v16, v15
	v_cndmask_b32_e64 v7, 0, v7, s[18:19]
	v_cndmask_b32_e32 v3, 0, v3, vcc
	v_cndmask_b32_e64 v1, 0, v1, s[20:21]
	v_cndmask_b32_e64 v9, 0, v9, s[22:23]
	v_cndmask_b32_e64 v10, 0, v10, s[24:25]
	v_cndmask_b32_e64 v11, 0, v11, s[26:27]
	v_cndmask_b32_e64 v14, 0, v14, s[28:29]
	v_cvt_pk_bf16_f32 v4, v3, v4
	v_cndmask_b32_e64 v15, 0, v15, s[30:31]
	v_lshlrev_b32_e32 v16, 16, v27
	v_mul_f32_e32 v16, v17, v16
	s_waitcnt lgkmcnt(5)
	v_sub_f32_e32 v17, v2, v18
	s_waitcnt lgkmcnt(4)
	v_sub_f32_e32 v18, v2, v19
	v_mul_f32_e32 v18, 0x3fb8aa3b, v18
	v_exp_f32_e32 v18, v18
	v_mul_f32_e32 v17, 0x3fb8aa3b, v17
	v_exp_f32_e32 v17, v17
	v_lshlrev_b32_e32 v8, 16, v8
	v_cndmask_b32_e64 v16, 0, v16, s[34:35]
	v_lshlrev_b32_e32 v5, 16, v5
	v_mul_f32_e32 v5, v18, v5
	v_cndmask_b32_e64 v18, 0, v5, s[38:39]
	v_lshlrev_b32_e32 v5, 16, v6
	s_waitcnt lgkmcnt(3)
	v_sub_f32_e32 v6, v2, v20
	v_mul_f32_e32 v8, v17, v8
	v_mul_f32_e32 v6, 0x3fb8aa3b, v6
	v_cndmask_b32_e64 v17, 0, v8, s[36:37]
	v_exp_f32_e32 v6, v6
	s_waitcnt lgkmcnt(2)
	v_sub_f32_e32 v8, v2, v21
	v_mul_f32_e32 v8, 0x3fb8aa3b, v8
	v_exp_f32_e32 v8, v8
	v_mul_f32_e32 v5, v6, v5
	v_cndmask_b32_e64 v19, 0, v5, s[40:41]
	v_lshlrev_b32_e32 v5, 16, v12
	s_waitcnt lgkmcnt(1)
	v_sub_f32_e32 v6, v2, v22
	v_mul_f32_e32 v5, v8, v5
	v_mul_f32_e32 v6, 0x3fb8aa3b, v6
	s_waitcnt lgkmcnt(0)
	v_sub_f32_e32 v8, v2, v23
	v_exp_f32_e32 v6, v6
	v_mul_f32_e32 v8, 0x3fb8aa3b, v8
	v_exp_f32_e32 v8, v8
	v_cndmask_b32_e64 v12, 0, v5, s[42:43]
	v_lshlrev_b32_e32 v5, 16, v13
	v_mul_f32_e32 v5, v6, v5
	v_lshlrev_b32_e32 v0, 16, v0
	v_cndmask_b32_e64 v13, 0, v5, s[44:45]
	v_mul_f32_e32 v0, v8, v0
	v_cvt_pk_bf16_f32 v5, v7, v1
	v_cvt_pk_bf16_f32 v6, v9, v10
	v_cvt_pk_bf16_f32 v7, v11, v14
	v_cndmask_b32_e64 v0, 0, v0, s[46:47]
	v_cvt_pk_bf16_f32 v8, v15, v16
	v_cvt_pk_bf16_f32 v9, v17, v18
	v_cvt_pk_bf16_f32 v10, v19, v12
	v_cvt_pk_bf16_f32 v11, v13, v0
	ds_write_b128 v115, v[4:7] offset:38912
	ds_write_b128 v115, v[8:11] offset:38928
	s_and_saveexec_b64 s[16:17], s[8:9]
	s_cbranch_execz .LBB0_1972
	v_mul_f32_e32 v0, 0x3fb8aa3b, v2
	v_exp_f32_e32 v2, v0
	s_ashr_i32 s79, s78, 31
	s_lshl_b64 s[18:19], s[78:79], 9
	v_lshl_add_u64 v[0:1], v[68:69], 0, s[18:19]
	global_store_dword v[0:1], v2, off
; __device__ __forceinline__ void gla_g1(const Params& P, unsigned char* lds) {
;     ...
;         f32x4 acc[8][2];
; #pragma unroll
;         for (int mt = 0; mt < 8; ++mt) { acc[mt][0] = (f32x4){0.f, 0.f, 0.f, 0.f}; acc[mt][1] = (f32x4){0.f, 0.f, 0.f, 0.f}; }
; #pragma unroll
;         for (int s = 0; s < 2; ++s) { const int t8 = 32 * s + 8 * fq;
;             if (32 * s < I.L) {
;                 bf16x8 bfr[2];
; #pragma unroll
;                 for (int nt = 0; nt < 2; ++nt) { const int tc = t8 < I.L ? t8 : 0; bfr[nt] = *(const bf16x8*)(vT + (size_t)(I.h * DV + 32 * wid + 16 * nt + fr) * MPAD + I.row0 + tc); if (t8 >= I.L) bfr[nt] = (bf16x8){0, 0, 0, 0, 0, 0, 0, 0}; }
; #pragma unroll
;                 for (int mt = 0; mt < 8; ++mt) { const bf16x8 a = *(const bf16x8*)(kT + (16 * mt + fr) * 72 + t8);
;                     acc[mt][0] = __builtin_amdgcn_mfma_f32_16x16x32_bf16(a, bfr[0], acc[mt][0], 0, 0, 0); acc[mt][1] = __builtin_amdgcn_mfma_f32_16x16x32_bf16(a, bfr[1], acc[mt][1], 0, 0, 0); } } }
.LBB0_1972:
	s_or_b64 exec, exec, s[16:17]
	s_ashr_i32 s83, s82, 31
	s_lshl_b64 s[16:17], s[82:83], 1
	v_cmp_gt_u32_e32 vcc, s64, v70
	s_add_u32 s18, s3, s16
	v_lshl_add_u32 v2, s65, 8, v116
	v_cndmask_b32_e32 v0, 0, v70, vcc
	s_addc_u32 s19, s85, s17
	v_lshlrev_b32_e32 v64, 1, v0
	v_lshl_add_u64 v[0:1], s[18:19], 0, v[64:65]
	v_mul_u32_u24_e32 v64, 0x8280, v2
	v_lshl_add_u64 v[4:5], v[0:1], 0, v[64:65]
	s_waitcnt lgkmcnt(0)
	s_barrier
	s_waitcnt vmcnt(2)
	v_mov_b32_e32 v0, v228
	v_mov_b32_e32 v1, v229
	v_mov_b32_e32 v2, v230
	v_mov_b32_e32 v3, v231
	v_add_co_u32_e64 v4, s[16:17], s84, v4
	v_cndmask_b32_e32 v3, 0, v3, vcc
	v_addc_co_u32_e64 v5, s[16:17], 0, v5, s[16:17]
	v_mov_b32_e32 v4, v232
	v_mov_b32_e32 v5, v233
	v_mov_b32_e32 v6, v234
	v_mov_b32_e32 v7, v235
	ds_read_b128 v[12:15], v149 offset:38912
	ds_read_b128 v[20:23], v149 offset:41216
	ds_read_b128 v[28:31], v149 offset:43520
	ds_read_b128 v[36:39], v149 offset:45824
	ds_read_b128 v[150:153], v149 offset:48128
	ds_read_b128 v[154:157], v149 offset:50432
	ds_read_b128 v[158:161], v149 offset:52736
	ds_read_b128 v[162:165], v149 offset:55040
	v_cndmask_b32_e32 v2, 0, v2, vcc
	v_cndmask_b32_e32 v1, 0, v1, vcc
	v_cndmask_b32_e32 v0, 0, v0, vcc
	v_cndmask_b32_e32 v7, 0, v7, vcc
	v_cndmask_b32_e32 v6, 0, v6, vcc
	v_cndmask_b32_e32 v5, 0, v5, vcc
	v_cndmask_b32_e32 v4, 0, v4, vcc
	s_waitcnt lgkmcnt(7)
	v_mfma_f32_16x16x32_bf16 v[56:59], v[12:15], v[0:3], 0
	s_andn2_b64 vcc, exec, s[80:81]
	s_waitcnt lgkmcnt(6)
	v_mfma_f32_16x16x32_bf16 v[48:51], v[20:23], v[0:3], 0
	s_waitcnt lgkmcnt(5)
	v_mfma_f32_16x16x32_bf16 v[40:43], v[28:31], v[0:3], 0
	s_waitcnt lgkmcnt(4)
	v_mfma_f32_16x16x32_bf16 v[32:35], v[36:39], v[0:3], 0
	s_waitcnt lgkmcnt(3)
	v_mfma_f32_16x16x32_bf16 v[24:27], v[150:153], v[0:3], 0
	s_waitcnt lgkmcnt(2)
	v_mfma_f32_16x16x32_bf16 v[16:19], v[154:157], v[0:3], 0
	s_waitcnt lgkmcnt(1)
	v_mfma_f32_16x16x32_bf16 v[8:11], v[158:161], v[0:3], 0
	s_waitcnt lgkmcnt(0)
	v_mfma_f32_16x16x32_bf16 v[0:3], v[162:165], v[0:3], 0
	v_mfma_f32_16x16x32_bf16 v[60:63], v[12:15], v[4:7], 0
	v_mfma_f32_16x16x32_bf16 v[52:55], v[20:23], v[4:7], 0
	v_mfma_f32_16x16x32_bf16 v[44:47], v[28:31], v[4:7], 0
	v_mfma_f32_16x16x32_bf16 v[36:39], v[36:39], v[4:7], 0
	v_mfma_f32_16x16x32_bf16 v[28:31], v[150:153], v[4:7], 0
	v_mfma_f32_16x16x32_bf16 v[20:23], v[154:157], v[4:7], 0
	v_mfma_f32_16x16x32_bf16 v[12:15], v[158:161], v[4:7], 0
	v_mfma_f32_16x16x32_bf16 v[4:7], v[162:165], v[4:7], 0
	s_cbranch_vccnz .LBB0_1961
	v_cmp_gt_u32_e64 s[16:17], s64, v71
	v_mov_b32_e32 v151, v65
	s_nop 0
	v_cndmask_b32_e64 v150, 0, v71, s[16:17]
	v_lshlrev_b32_e32 v150, 1, v150
	v_lshl_add_u64 v[150:151], s[18:19], 0, v[150:151]
	v_lshl_add_u64 v[154:155], v[150:151], 0, v[64:65]
	s_waitcnt vmcnt(0)
	v_mov_b32_e32 v150, v236
	v_mov_b32_e32 v151, v237
	v_mov_b32_e32 v152, v238
	v_mov_b32_e32 v153, v239
	v_add_co_u32_e32 v154, vcc, 0x82000, v154
	v_cndmask_b32_e64 v153, 0, v153, s[16:17]
	v_addc_co_u32_e32 v155, vcc, 0, v155, vcc
	v_mov_b32_e32 v154, v244
	v_mov_b32_e32 v155, v245
	v_mov_b32_e32 v156, v246
	v_mov_b32_e32 v157, v247
	ds_read_b128 v[158:161], v149 offset:38976
	ds_read_b128 v[162:165], v149 offset:41280
	ds_read_b128 v[166:169], v149 offset:43584
	ds_read_b128 v[170:173], v149 offset:45888
	ds_read_b128 v[174:177], v149 offset:48192
	ds_read_b128 v[178:181], v149 offset:50496
	ds_read_b128 v[182:185], v149 offset:52800
	ds_read_b128 v[186:189], v149 offset:55104
	v_cndmask_b32_e64 v152, 0, v152, s[16:17]
	v_cndmask_b32_e64 v151, 0, v151, s[16:17]
	v_cndmask_b32_e64 v150, 0, v150, s[16:17]
	s_waitcnt lgkmcnt(7)
	s_nop 0
	v_mfma_f32_16x16x32_bf16 v[56:59], v[158:161], v[150:153], v[56:59]
	s_waitcnt lgkmcnt(6)
	v_mfma_f32_16x16x32_bf16 v[48:51], v[162:165], v[150:153], v[48:51]
	s_waitcnt lgkmcnt(5)
	v_mfma_f32_16x16x32_bf16 v[40:43], v[166:169], v[150:153], v[40:43]
	s_waitcnt lgkmcnt(4)
	v_mfma_f32_16x16x32_bf16 v[32:35], v[170:173], v[150:153], v[32:35]
	s_waitcnt lgkmcnt(3)
	v_mfma_f32_16x16x32_bf16 v[24:27], v[174:177], v[150:153], v[24:27]
	s_waitcnt lgkmcnt(2)
	v_mfma_f32_16x16x32_bf16 v[16:19], v[178:181], v[150:153], v[16:19]
	s_waitcnt lgkmcnt(1)
	v_mfma_f32_16x16x32_bf16 v[8:11], v[182:185], v[150:153], v[8:11]
	s_waitcnt lgkmcnt(0)
	v_mfma_f32_16x16x32_bf16 v[0:3], v[186:189], v[150:153], v[0:3]
	v_cndmask_b32_e64 v153, 0, v157, s[16:17]
	v_cndmask_b32_e64 v152, 0, v156, s[16:17]
	v_cndmask_b32_e64 v151, 0, v155, s[16:17]
	v_cndmask_b32_e64 v150, 0, v154, s[16:17]
	s_nop 1
	v_mfma_f32_16x16x32_bf16 v[60:63], v[158:161], v[150:153], v[60:63]
	v_mfma_f32_16x16x32_bf16 v[52:55], v[162:165], v[150:153], v[52:55]
	v_mfma_f32_16x16x32_bf16 v[44:47], v[166:169], v[150:153], v[44:47]
	v_mfma_f32_16x16x32_bf16 v[36:39], v[170:173], v[150:153], v[36:39]
	v_mfma_f32_16x16x32_bf16 v[28:31], v[174:177], v[150:153], v[28:31]
	v_mfma_f32_16x16x32_bf16 v[20:23], v[178:181], v[150:153], v[20:23]
	v_mfma_f32_16x16x32_bf16 v[12:15], v[182:185], v[150:153], v[12:15]
	v_mfma_f32_16x16x32_bf16 v[4:7], v[186:189], v[150:153], v[4:7]
	s_branch .LBB0_1961

; __device__ __forceinline__ Item decode_item(int it) { Item I; if (it < 1024) { const int b = it >> 8; I.h = (it >> 6) & 3; I.row0 = b * SEQ + (it & 63) * 64; I.L = 64; } else { const int j = it - 1024; I.h = j & 3; I.row0 = MP_ROWS + (j >> 2) * 16; I.L = 16; } I.j = it; return I; }
; __device__ __forceinline__ void gla_g1(const Params& P, unsigned char* lds) {
;     ...
;     for (int it = blockIdx.x; it < NITEM; it += gridDim.x) {
;         const Item I = decode_item(it);
;         compute_b(P, I, lds);
.LBB0_1975:
	s_and_b32 s16, s88, 0xfffff000
	s_and_b32 s17, s90, 0xfc0
	s_lshr_b32 s18, s78, 6
	s_or_b32 s82, s16, s17
	s_mov_b32 s64, 64
	s_branch .LBB0_1964

; __global__ void __launch_bounds__(NT, 2) fwd_kernel(Params P) {
	.amdhsa_kernel _Z10fwd_kernel6Params
		.amdhsa_group_segment_fixed_size 0
		.amdhsa_private_segment_fixed_size 0
		.amdhsa_kernarg_size 464
		.amdhsa_user_sgpr_count 2
		.amdhsa_user_sgpr_dispatch_ptr 0
		.amdhsa_user_sgpr_queue_ptr 0
		.amdhsa_user_sgpr_kernarg_segment_ptr 1
		.amdhsa_user_sgpr_dispatch_id 0
		.amdhsa_user_sgpr_kernarg_preload_length 0
		.amdhsa_user_sgpr_kernarg_preload_offset 0
		.amdhsa_user_sgpr_private_segment_size 0
		.amdhsa_uses_dynamic_stack 0
		.amdhsa_enable_private_segment 0
		.amdhsa_system_sgpr_workgroup_id_x 1
		.amdhsa_system_sgpr_workgroup_id_y 0
		.amdhsa_system_sgpr_workgroup_id_z 0
		.amdhsa_system_sgpr_workgroup_info 0
		.amdhsa_system_vgpr_workitem_id 2
		.amdhsa_next_free_vgpr 248
		.amdhsa_next_free_sgpr 102
		.amdhsa_accum_offset 248
		.amdhsa_reserve_vcc 1
		.amdhsa_float_round_mode_32 0
		.amdhsa_float_round_mode_16_64 0
		.amdhsa_float_denorm_mode_32 3
		.amdhsa_float_denorm_mode_16_64 3
		.amdhsa_dx10_clamp 1
		.amdhsa_ieee_mode 1
		.amdhsa_fp16_overflow 0
		.amdhsa_tg_split 0
		.amdhsa_exception_fp_ieee_invalid_op 0
		.amdhsa_exception_fp_denorm_src 0
		.amdhsa_exception_fp_ieee_div_zero 0
		.amdhsa_exception_fp_ieee_overflow 0
		.amdhsa_exception_fp_ieee_underflow 0
		.amdhsa_exception_fp_ieee_inexact 0
		.amdhsa_exception_int_div_zero 0
	.end_amdhsa_kernel

; __global__ void __launch_bounds__(NT, 2) fwd_kernel(Params P) {
amdhsa.kernels:
  - .agpr_count:     0
    .args:
      - .offset:         0
        .size:           208
        .value_kind:     by_value
      - .offset:         208
        .size:           4
        .value_kind:     hidden_block_count_x
      - .offset:         212
        .size:           4
        .value_kind:     hidden_block_count_y
      - .offset:         216
        .size:           4
        .value_kind:     hidden_block_count_z
      - .offset:         220
        .size:           2
        .value_kind:     hidden_group_size_x
      - .offset:         222
        .size:           2
        .value_kind:     hidden_group_size_y
      - .offset:         224
        .size:           2
        .value_kind:     hidden_group_size_z
      - .offset:         226
        .size:           2
        .value_kind:     hidden_remainder_x
      - .offset:         228
        .size:           2
        .value_kind:     hidden_remainder_y
      - .offset:         230
        .size:           2
        .value_kind:     hidden_remainder_z
      - .offset:         248
        .size:           8
        .value_kind:     hidden_global_offset_x
      - .offset:         256
        .size:           8
        .value_kind:     hidden_global_offset_y
      - .offset:         264
        .size:           8
        .value_kind:     hidden_global_offset_z
      - .offset:         272
        .size:           2
        .value_kind:     hidden_grid_dims
      - .offset:         296
        .size:           8
        .value_kind:     hidden_multigrid_sync_arg
      - .offset:         328
        .size:           4
        .value_kind:     hidden_dynamic_lds_size
    .group_segment_fixed_size: 0
    .kernarg_segment_align: 8
    .kernarg_segment_size: 464
    .language:       OpenCL C
    .language_version:
      - 2
      - 0
    .max_flat_workgroup_size: 512
    .name:           _Z10fwd_kernel6Params
    .private_segment_fixed_size: 0
    .sgpr_count:     108
    .sgpr_spill_count: 6
    .symbol:         _Z10fwd_kernel6Params.kd
    .uniform_work_group_size: 1
    .uses_dynamic_stack: false
    .vgpr_count:     248
    .vgpr_spill_count: 0
    .wavefront_size: 64
